# local seams: L1 invalidate issued right after the arrival flag store (overlaps the wait for the other workgroups) instead of after the release
# speedup vs baseline: 1.0242x; 1.0052x over previous
; __device__ __forceinline__ unsigned xb_ld(unsigned* p)              { return __hip_atomic_load(p, __ATOMIC_RELAXED, __HIP_MEMORY_SCOPE_AGENT); }
; __device__ __forceinline__ unsigned xb_add(unsigned* p, unsigned v) { return __hip_atomic_fetch_add(p, v, __ATOMIC_RELAXED, __HIP_MEMORY_SCOPE_AGENT); }
; #define XB_SPIN(cond, bar) do { unsigned _sp = 0; while (cond) { __builtin_amdgcn_s_sleep(1); \
;     if ((++_sp & 255u) == 0u) { if (xb_ld(&(bar)[XB_TMO])) break; if (_sp > XB_SPIN_CAP) { atomicAdd(&(bar)[XB_TMO], 1u); break; } } } } while (0)
; __device__ __forceinline__ void xcd_barrier(const XcdBarrier& b) {
;     asm volatile("s_waitcnt vmcnt(0)" ::: "memory");
;     __syncthreads();
;     if (threadIdx.x == 0) {
;         unsigned* bar = b.bar;
;         __builtin_amdgcn_s_waitcnt(0);
;         unsigned nloc = b.st[0], nx = b.st[1];
;         if (nloc == 0u) { xcd_barrier_complete(bar, b.x, nloc, nx); b.st[0] = nloc; b.st[1] = nx; }
;         const unsigned old = xb_add(&bar[XB_XSUB(b.x)], 1u);
;         const unsigned gen = old / nloc;
;         if (old + 1u == (gen + 1u) * nloc) {
;             __builtin_amdgcn_fence(__ATOMIC_RELEASE, "agent");
;             asm volatile("s_waitcnt vmcnt(0)" ::: "memory");
;             const unsigned og = xb_add(&bar[XB_TOP], 1u);
;             const unsigned tg = og / nx;
;             if (og + 1u == (tg + 1u) * nx) xb_add(&bar[XB_TOPGEN], 1u);
;             else XB_SPIN(xb_ld(&bar[XB_TOPGEN]) == tg, bar);
;             __builtin_amdgcn_fence(__ATOMIC_ACQUIRE, "agent");
;             xb_add(&bar[XB_XGEN(b.x)], 1u);
;             asm volatile("s_waitcnt vmcnt(0)" ::: "memory");
;         } else {
;             XB_SPIN(xb_ld(&bar[XB_XGEN(b.x)]) == gen, bar);
;             __builtin_amdgcn_fence(__ATOMIC_ACQUIRE, "agent");
;             asm volatile("s_waitcnt vmcnt(0)" ::: "memory");
;         }
.LBB0_344:
	s_cmp_lt_i32 s92, 3
	s_cselect_b64 s[8:9], -1, 0
	s_cmp_gt_i32 s93, 2
	s_cselect_b64 s[0:1], -1, 0
	s_and_b64 s[0:1], s[8:9], s[0:1]
	s_andn2_b64 vcc, exec, s[0:1]
	s_cbranch_vccnz .LBB0_441
	s_andn2_b64 vcc, exec, s[10:11]
	s_cbranch_vccnz .LBB0_395
	s_waitcnt vmcnt(0)
	v_cmp_eq_u32_e32 vcc, 0, v254
	s_waitcnt vmcnt(0) lgkmcnt(0)
	s_barrier
	s_and_saveexec_b64 s[0:1], vcc
	s_cbranch_execz .LBB0_394
	s_cmp_eq_u32 s98, 1
	s_cbranch_scc0 .Lxfull_2
	s_add_i32 s99, s99, 1
	s_and_b32 s4, s2, 7
	s_lshl_b32 s4, s4, 8
	s_add_u32 s4, s90, s4
	s_addc_u32 s5, s91, 0
	s_lshr_b32 s3, s2, 3
	v_mov_b32_e32 v0, s99
	v_mov_b32_e32 v1, s3
	v_lshlrev_b32_e32 v1, 2, v1
	global_store_dword v1, v0, s[4:5] offset:512
	buffer_inv sc1
	s_cmp_eq_u32 s3, 0
	s_cbranch_scc0 .Lxwait_2
	s_mov_b64 s[6:7], exec
	s_mov_b32 exec_lo, -1
	s_mov_b32 exec_hi, 0
	v_lshlrev_b32_e32 v2, 2, v251
	s_mov_b32 s3, 0

; __device__ __forceinline__ unsigned xb_ld(unsigned* p)              { return __hip_atomic_load(p, __ATOMIC_RELAXED, __HIP_MEMORY_SCOPE_AGENT); }
; __device__ __forceinline__ unsigned xb_add(unsigned* p, unsigned v) { return __hip_atomic_fetch_add(p, v, __ATOMIC_RELAXED, __HIP_MEMORY_SCOPE_AGENT); }
; #define XB_SPIN(cond, bar) do { unsigned _sp = 0; while (cond) { __builtin_amdgcn_s_sleep(1); \
;     if ((++_sp & 255u) == 0u) { if (xb_ld(&(bar)[XB_TMO])) break; if (_sp > XB_SPIN_CAP) { atomicAdd(&(bar)[XB_TMO], 1u); break; } } } } while (0)
; __device__ __forceinline__ void xcd_barrier(const XcdBarrier& b) {
;     ...
;             __builtin_amdgcn_fence(__ATOMIC_ACQUIRE, "agent");
;             xb_add(&bar[XB_XGEN(b.x)], 1u);
;             asm volatile("s_waitcnt vmcnt(0)" ::: "memory");
;         } else {
;             XB_SPIN(xb_ld(&bar[XB_XGEN(b.x)]) == gen, bar);
;             __builtin_amdgcn_fence(__ATOMIC_ACQUIRE, "agent");
;             asm volatile("s_waitcnt vmcnt(0)" ::: "memory");
;         }
.Lxfin_2:
	s_waitcnt vmcnt(0)
	s_branch .LBB0_394

; __device__ __forceinline__ unsigned xb_ld(unsigned* p)              { return __hip_atomic_load(p, __ATOMIC_RELAXED, __HIP_MEMORY_SCOPE_AGENT); }
; __device__ __forceinline__ unsigned xb_add(unsigned* p, unsigned v) { return __hip_atomic_fetch_add(p, v, __ATOMIC_RELAXED, __HIP_MEMORY_SCOPE_AGENT); }
; #define XB_SPIN(cond, bar) do { unsigned _sp = 0; while (cond) { __builtin_amdgcn_s_sleep(1); \
;     if ((++_sp & 255u) == 0u) { if (xb_ld(&(bar)[XB_TMO])) break; if (_sp > XB_SPIN_CAP) { atomicAdd(&(bar)[XB_TMO], 1u); break; } } } } while (0)
; __device__ __forceinline__ void xcd_barrier(const XcdBarrier& b) {
;     asm volatile("s_waitcnt vmcnt(0)" ::: "memory");
;     __syncthreads();
;     if (threadIdx.x == 0) {
;         unsigned* bar = b.bar;
;         __builtin_amdgcn_s_waitcnt(0);
;         unsigned nloc = b.st[0], nx = b.st[1];
;         if (nloc == 0u) { xcd_barrier_complete(bar, b.x, nloc, nx); b.st[0] = nloc; b.st[1] = nx; }
;         const unsigned old = xb_add(&bar[XB_XSUB(b.x)], 1u);
;         const unsigned gen = old / nloc;
;         if (old + 1u == (gen + 1u) * nloc) {
;             __builtin_amdgcn_fence(__ATOMIC_RELEASE, "agent");
;             asm volatile("s_waitcnt vmcnt(0)" ::: "memory");
;             const unsigned og = xb_add(&bar[XB_TOP], 1u);
;             const unsigned tg = og / nx;
;             if (og + 1u == (tg + 1u) * nx) xb_add(&bar[XB_TOPGEN], 1u);
;             else XB_SPIN(xb_ld(&bar[XB_TOPGEN]) == tg, bar);
;             __builtin_amdgcn_fence(__ATOMIC_ACQUIRE, "agent");
;             xb_add(&bar[XB_XGEN(b.x)], 1u);
;             asm volatile("s_waitcnt vmcnt(0)" ::: "memory");
;         } else {
;             XB_SPIN(xb_ld(&bar[XB_XGEN(b.x)]) == gen, bar);
;             __builtin_amdgcn_fence(__ATOMIC_ACQUIRE, "agent");
;             asm volatile("s_waitcnt vmcnt(0)" ::: "memory");
;         }
.LBB0_441:
	s_cmp_lt_i32 s92, 4
	s_cselect_b64 s[10:11], -1, 0
	s_cmp_gt_i32 s93, 3
	s_cselect_b64 s[0:1], -1, 0
	s_and_b64 s[0:1], s[10:11], s[0:1]
	s_andn2_b64 vcc, exec, s[0:1]
	s_cbranch_vccnz .LBB0_622
	s_andn2_b64 vcc, exec, s[8:9]
	s_cbranch_vccnz .LBB0_492
	s_waitcnt vmcnt(0)
	v_cmp_eq_u32_e32 vcc, 0, v254
	s_waitcnt vmcnt(0) lgkmcnt(0)
	s_barrier
	s_and_saveexec_b64 s[0:1], vcc
	s_cbranch_execz .LBB0_491
	s_cmp_eq_u32 s98, 1
	s_cbranch_scc0 .Lxfull_3
	s_add_i32 s99, s99, 1
	s_and_b32 s4, s2, 7
	s_lshl_b32 s4, s4, 8
	s_add_u32 s4, s90, s4
	s_addc_u32 s5, s91, 0
	s_lshr_b32 s3, s2, 3
	v_mov_b32_e32 v0, s99
	v_mov_b32_e32 v1, s3
	v_lshlrev_b32_e32 v1, 2, v1
	global_store_dword v1, v0, s[4:5] offset:512
	buffer_inv sc1
	s_cmp_eq_u32 s3, 0
	s_cbranch_scc0 .Lxwait_3
	s_mov_b64 s[6:7], exec
	s_mov_b32 exec_lo, -1
	s_mov_b32 exec_hi, 0
	v_lshlrev_b32_e32 v2, 2, v251
	s_mov_b32 s3, 0

; __device__ __forceinline__ unsigned xb_ld(unsigned* p)              { return __hip_atomic_load(p, __ATOMIC_RELAXED, __HIP_MEMORY_SCOPE_AGENT); }
; __device__ __forceinline__ unsigned xb_add(unsigned* p, unsigned v) { return __hip_atomic_fetch_add(p, v, __ATOMIC_RELAXED, __HIP_MEMORY_SCOPE_AGENT); }
; #define XB_SPIN(cond, bar) do { unsigned _sp = 0; while (cond) { __builtin_amdgcn_s_sleep(1); \
;     if ((++_sp & 255u) == 0u) { if (xb_ld(&(bar)[XB_TMO])) break; if (_sp > XB_SPIN_CAP) { atomicAdd(&(bar)[XB_TMO], 1u); break; } } } } while (0)
; __device__ __forceinline__ void xcd_barrier(const XcdBarrier& b) {
;     asm volatile("s_waitcnt vmcnt(0)" ::: "memory");
;     __syncthreads();
;     if (threadIdx.x == 0) {
;         unsigned* bar = b.bar;
;         __builtin_amdgcn_s_waitcnt(0);
;         unsigned nloc = b.st[0], nx = b.st[1];
;         if (nloc == 0u) { xcd_barrier_complete(bar, b.x, nloc, nx); b.st[0] = nloc; b.st[1] = nx; }
;         const unsigned old = xb_add(&bar[XB_XSUB(b.x)], 1u);
;         const unsigned gen = old / nloc;
;         if (old + 1u == (gen + 1u) * nloc) {
;             __builtin_amdgcn_fence(__ATOMIC_RELEASE, "agent");
;             asm volatile("s_waitcnt vmcnt(0)" ::: "memory");
;             const unsigned og = xb_add(&bar[XB_TOP], 1u);
;             const unsigned tg = og / nx;
;             if (og + 1u == (tg + 1u) * nx) xb_add(&bar[XB_TOPGEN], 1u);
;             else XB_SPIN(xb_ld(&bar[XB_TOPGEN]) == tg, bar);
;             __builtin_amdgcn_fence(__ATOMIC_ACQUIRE, "agent");
;             xb_add(&bar[XB_XGEN(b.x)], 1u);
;             asm volatile("s_waitcnt vmcnt(0)" ::: "memory");
;         } else {
;             XB_SPIN(xb_ld(&bar[XB_XGEN(b.x)]) == gen, bar);
;             __builtin_amdgcn_fence(__ATOMIC_ACQUIRE, "agent");
;             asm volatile("s_waitcnt vmcnt(0)" ::: "memory");
;         }
.LBB0_704:
	s_cmp_lt_i32 s92, 6
	s_cselect_b64 s[0:1], -1, 0
	s_cmp_gt_i32 s93, 5
	s_cselect_b64 s[4:5], -1, 0
	s_and_b64 s[4:5], s[0:1], s[4:5]
	v_readlane_b32 s64, v255, 4
	s_andn2_b64 vcc, exec, s[4:5]
	v_readlane_b32 s68, v255, 8
	v_readlane_b32 s69, v255, 9
	v_readlane_b32 s65, v255, 5
	v_readlane_b32 s66, v255, 6
	v_readlane_b32 s67, v255, 7
	v_readlane_b32 s70, v255, 10
	v_readlane_b32 s71, v255, 11
	v_readlane_b32 s72, v255, 12
	v_readlane_b32 s73, v255, 13
	v_readlane_b32 s74, v255, 14
	v_readlane_b32 s75, v255, 15
	v_readlane_b32 s76, v255, 16
	v_readlane_b32 s77, v255, 17
	v_readlane_b32 s78, v255, 18
	v_readlane_b32 s79, v255, 19
	s_cbranch_vccnz .LBB0_765
	s_andn2_b64 vcc, exec, s[80:81]
	s_cbranch_vccnz .LBB0_755
	s_waitcnt vmcnt(0)
	v_cmp_eq_u32_e32 vcc, 0, v254
	s_waitcnt vmcnt(0) lgkmcnt(0)
	s_barrier
	s_and_saveexec_b64 s[4:5], vcc
	s_cbranch_execz .LBB0_754
	s_cmp_eq_u32 s98, 1
	s_cbranch_scc0 .Lxfull_5
	s_add_i32 s99, s99, 1
	s_and_b32 s6, s2, 7
	s_lshl_b32 s6, s6, 8
	s_add_u32 s6, s90, s6
	s_addc_u32 s7, s91, 0
	s_lshr_b32 s3, s2, 3
	v_mov_b32_e32 v0, s99
	v_mov_b32_e32 v1, s3
	v_lshlrev_b32_e32 v1, 2, v1
	global_store_dword v1, v0, s[6:7] offset:512
	buffer_inv sc1
	s_cmp_eq_u32 s3, 0
	s_cbranch_scc0 .Lxwait_5
	s_mov_b64 s[8:9], exec
	s_mov_b32 exec_lo, -1
	s_mov_b32 exec_hi, 0
	v_lshlrev_b32_e32 v2, 2, v251
	s_mov_b32 s3, 0

; __device__ __forceinline__ unsigned xb_ld(unsigned* p)              { return __hip_atomic_load(p, __ATOMIC_RELAXED, __HIP_MEMORY_SCOPE_AGENT); }
; __device__ __forceinline__ unsigned xb_add(unsigned* p, unsigned v) { return __hip_atomic_fetch_add(p, v, __ATOMIC_RELAXED, __HIP_MEMORY_SCOPE_AGENT); }
; #define XB_SPIN(cond, bar) do { unsigned _sp = 0; while (cond) { __builtin_amdgcn_s_sleep(1); \
;     if ((++_sp & 255u) == 0u) { if (xb_ld(&(bar)[XB_TMO])) break; if (_sp > XB_SPIN_CAP) { atomicAdd(&(bar)[XB_TMO], 1u); break; } } } } while (0)
; __device__ __forceinline__ void xcd_barrier(const XcdBarrier& b) {
;     asm volatile("s_waitcnt vmcnt(0)" ::: "memory");
;     __syncthreads();
;     if (threadIdx.x == 0) {
;         unsigned* bar = b.bar;
;         __builtin_amdgcn_s_waitcnt(0);
;         unsigned nloc = b.st[0], nx = b.st[1];
;         if (nloc == 0u) { xcd_barrier_complete(bar, b.x, nloc, nx); b.st[0] = nloc; b.st[1] = nx; }
;         const unsigned old = xb_add(&bar[XB_XSUB(b.x)], 1u);
;         const unsigned gen = old / nloc;
;         if (old + 1u == (gen + 1u) * nloc) {
;             __builtin_amdgcn_fence(__ATOMIC_RELEASE, "agent");
;             asm volatile("s_waitcnt vmcnt(0)" ::: "memory");
;             const unsigned og = xb_add(&bar[XB_TOP], 1u);
;             const unsigned tg = og / nx;
;             if (og + 1u == (tg + 1u) * nx) xb_add(&bar[XB_TOPGEN], 1u);
;             else XB_SPIN(xb_ld(&bar[XB_TOPGEN]) == tg, bar);
;             __builtin_amdgcn_fence(__ATOMIC_ACQUIRE, "agent");
;             xb_add(&bar[XB_XGEN(b.x)], 1u);
;             asm volatile("s_waitcnt vmcnt(0)" ::: "memory");
;         } else {
;             XB_SPIN(xb_ld(&bar[XB_XGEN(b.x)]) == gen, bar);
;             __builtin_amdgcn_fence(__ATOMIC_ACQUIRE, "agent");
;             asm volatile("s_waitcnt vmcnt(0)" ::: "memory");
;         }
.LBB0_765:
	s_cmp_lt_i32 s92, 7
	s_cselect_b64 s[40:41], -1, 0
	s_cmp_gt_i32 s93, 6
	s_cselect_b64 s[4:5], -1, 0
	s_and_b64 s[4:5], s[40:41], s[4:5]
	s_andn2_b64 vcc, exec, s[4:5]
	s_cbranch_vccnz .LBB0_890
	s_andn2_b64 vcc, exec, s[0:1]
	s_cbranch_vccnz .LBB0_816
	s_waitcnt vmcnt(0)
	v_cmp_eq_u32_e32 vcc, 0, v254
	s_waitcnt vmcnt(0) lgkmcnt(0)
	s_barrier
	s_and_saveexec_b64 s[0:1], vcc
	s_cbranch_execz .LBB0_815
	s_cmp_eq_u32 s98, 1
	s_cbranch_scc0 .Lxfull_6
	s_add_i32 s99, s99, 1
	s_and_b32 s4, s2, 7
	s_lshl_b32 s4, s4, 8
	s_add_u32 s4, s90, s4
	s_addc_u32 s5, s91, 0
	s_lshr_b32 s3, s2, 3
	v_mov_b32_e32 v0, s99
	v_mov_b32_e32 v1, s3
	v_lshlrev_b32_e32 v1, 2, v1
	global_store_dword v1, v0, s[4:5] offset:512
	buffer_inv sc1
	s_cmp_eq_u32 s3, 0
	s_cbranch_scc0 .Lxwait_6
	s_mov_b64 s[6:7], exec
	s_mov_b32 exec_lo, -1
	s_mov_b32 exec_hi, 0
	v_lshlrev_b32_e32 v2, 2, v251
	s_mov_b32 s3, 0

; __device__ __forceinline__ unsigned xb_ld(unsigned* p)              { return __hip_atomic_load(p, __ATOMIC_RELAXED, __HIP_MEMORY_SCOPE_AGENT); }
; __device__ __forceinline__ unsigned xb_add(unsigned* p, unsigned v) { return __hip_atomic_fetch_add(p, v, __ATOMIC_RELAXED, __HIP_MEMORY_SCOPE_AGENT); }
; #define XB_SPIN(cond, bar) do { unsigned _sp = 0; while (cond) { __builtin_amdgcn_s_sleep(1); \
;     if ((++_sp & 255u) == 0u) { if (xb_ld(&(bar)[XB_TMO])) break; if (_sp > XB_SPIN_CAP) { atomicAdd(&(bar)[XB_TMO], 1u); break; } } } } while (0)
; __device__ __forceinline__ void xcd_barrier(const XcdBarrier& b) {
;     asm volatile("s_waitcnt vmcnt(0)" ::: "memory");
;     __syncthreads();
;     if (threadIdx.x == 0) {
;         unsigned* bar = b.bar;
;         __builtin_amdgcn_s_waitcnt(0);
;         unsigned nloc = b.st[0], nx = b.st[1];
;         if (nloc == 0u) { xcd_barrier_complete(bar, b.x, nloc, nx); b.st[0] = nloc; b.st[1] = nx; }
;         const unsigned old = xb_add(&bar[XB_XSUB(b.x)], 1u);
;         const unsigned gen = old / nloc;
;         if (old + 1u == (gen + 1u) * nloc) {
;             __builtin_amdgcn_fence(__ATOMIC_RELEASE, "agent");
;             asm volatile("s_waitcnt vmcnt(0)" ::: "memory");
;             const unsigned og = xb_add(&bar[XB_TOP], 1u);
;             const unsigned tg = og / nx;
;             if (og + 1u == (tg + 1u) * nx) xb_add(&bar[XB_TOPGEN], 1u);
;             else XB_SPIN(xb_ld(&bar[XB_TOPGEN]) == tg, bar);
;             __builtin_amdgcn_fence(__ATOMIC_ACQUIRE, "agent");
;             xb_add(&bar[XB_XGEN(b.x)], 1u);
;             asm volatile("s_waitcnt vmcnt(0)" ::: "memory");
;         } else {
;             XB_SPIN(xb_ld(&bar[XB_XGEN(b.x)]) == gen, bar);
;             __builtin_amdgcn_fence(__ATOMIC_ACQUIRE, "agent");
;             asm volatile("s_waitcnt vmcnt(0)" ::: "memory");
;         }
.LBB0_983:
	s_cmp_lt_i32 s92, 9
	s_cselect_b64 s[10:11], -1, 0
	s_cmp_gt_i32 s93, 8
	s_cselect_b64 s[0:1], -1, 0
	s_and_b64 s[0:1], s[10:11], s[0:1]
	s_andn2_b64 vcc, exec, s[0:1]
	s_cbranch_vccnz .LBB0_1056
	s_andn2_b64 vcc, exec, s[6:7]
	s_cbranch_vccnz .LBB0_1034
	s_waitcnt vmcnt(0)
	v_cmp_eq_u32_e32 vcc, 0, v254
	s_waitcnt vmcnt(0) lgkmcnt(0)
	s_barrier
	s_and_saveexec_b64 s[0:1], vcc
	s_cbranch_execz .LBB0_1033
	s_cmp_eq_u32 s98, 1
	s_cbranch_scc0 .Lxfull_8
	s_add_i32 s99, s99, 1
	s_and_b32 s4, s2, 7
	s_lshl_b32 s4, s4, 8
	s_add_u32 s4, s90, s4
	s_addc_u32 s5, s91, 0
	s_lshr_b32 s3, s2, 3
	v_mov_b32_e32 v0, s99
	v_mov_b32_e32 v1, s3
	v_lshlrev_b32_e32 v1, 2, v1
	global_store_dword v1, v0, s[4:5] offset:512
	buffer_inv sc1
	s_cmp_eq_u32 s3, 0
	s_cbranch_scc0 .Lxwait_8
	s_mov_b64 s[6:7], exec
	s_mov_b32 exec_lo, -1
	s_mov_b32 exec_hi, 0
	v_lshlrev_b32_e32 v2, 2, v251
	s_mov_b32 s3, 0

; __device__ __forceinline__ unsigned xb_ld(unsigned* p)              { return __hip_atomic_load(p, __ATOMIC_RELAXED, __HIP_MEMORY_SCOPE_AGENT); }
; __device__ __forceinline__ unsigned xb_add(unsigned* p, unsigned v) { return __hip_atomic_fetch_add(p, v, __ATOMIC_RELAXED, __HIP_MEMORY_SCOPE_AGENT); }
; #define XB_SPIN(cond, bar) do { unsigned _sp = 0; while (cond) { __builtin_amdgcn_s_sleep(1); \
;     if ((++_sp & 255u) == 0u) { if (xb_ld(&(bar)[XB_TMO])) break; if (_sp > XB_SPIN_CAP) { atomicAdd(&(bar)[XB_TMO], 1u); break; } } } } while (0)
; __device__ __forceinline__ void xcd_barrier(const XcdBarrier& b) {
;     asm volatile("s_waitcnt vmcnt(0)" ::: "memory");
;     __syncthreads();
;     if (threadIdx.x == 0) {
;         unsigned* bar = b.bar;
;         __builtin_amdgcn_s_waitcnt(0);
;         unsigned nloc = b.st[0], nx = b.st[1];
;         if (nloc == 0u) { xcd_barrier_complete(bar, b.x, nloc, nx); b.st[0] = nloc; b.st[1] = nx; }
;         const unsigned old = xb_add(&bar[XB_XSUB(b.x)], 1u);
;         const unsigned gen = old / nloc;
;         if (old + 1u == (gen + 1u) * nloc) {
;             __builtin_amdgcn_fence(__ATOMIC_RELEASE, "agent");
;             asm volatile("s_waitcnt vmcnt(0)" ::: "memory");
;             const unsigned og = xb_add(&bar[XB_TOP], 1u);
;             const unsigned tg = og / nx;
;             if (og + 1u == (tg + 1u) * nx) xb_add(&bar[XB_TOPGEN], 1u);
;             else XB_SPIN(xb_ld(&bar[XB_TOPGEN]) == tg, bar);
;             __builtin_amdgcn_fence(__ATOMIC_ACQUIRE, "agent");
;             xb_add(&bar[XB_XGEN(b.x)], 1u);
;             asm volatile("s_waitcnt vmcnt(0)" ::: "memory");
;         } else {
;             XB_SPIN(xb_ld(&bar[XB_XGEN(b.x)]) == gen, bar);
;             __builtin_amdgcn_fence(__ATOMIC_ACQUIRE, "agent");
;             asm volatile("s_waitcnt vmcnt(0)" ::: "memory");
;         }
.LBB0_1056:
	s_cmp_lt_i32 s92, 10
	s_cselect_b64 s[8:9], -1, 0
	s_cmp_gt_i32 s93, 9
	s_cselect_b64 s[0:1], -1, 0
	s_and_b64 s[0:1], s[8:9], s[0:1]
	s_andn2_b64 vcc, exec, s[0:1]
	s_cbranch_vccnz .LBB0_1153
	s_andn2_b64 vcc, exec, s[10:11]
	s_cbranch_vccnz .LBB0_1107
	s_waitcnt vmcnt(0)
	v_cmp_eq_u32_e32 vcc, 0, v254
	s_waitcnt vmcnt(0) lgkmcnt(0)
	s_barrier
	s_and_saveexec_b64 s[0:1], vcc
	s_cbranch_execz .LBB0_1106
	s_cmp_eq_u32 s98, 1
	s_cbranch_scc0 .Lxfull_9
	s_add_i32 s99, s99, 1
	s_and_b32 s4, s2, 7
	s_lshl_b32 s4, s4, 8
	s_add_u32 s4, s90, s4
	s_addc_u32 s5, s91, 0
	s_lshr_b32 s3, s2, 3
	v_mov_b32_e32 v0, s99
	v_mov_b32_e32 v1, s3
	v_lshlrev_b32_e32 v1, 2, v1
	global_store_dword v1, v0, s[4:5] offset:512
	buffer_inv sc1
	s_cmp_eq_u32 s3, 0
	s_cbranch_scc0 .Lxwait_9
	s_mov_b64 s[6:7], exec
	s_mov_b32 exec_lo, -1
	s_mov_b32 exec_hi, 0
	v_lshlrev_b32_e32 v2, 2, v251
	s_mov_b32 s3, 0

; __device__ __forceinline__ unsigned xb_ld(unsigned* p)              { return __hip_atomic_load(p, __ATOMIC_RELAXED, __HIP_MEMORY_SCOPE_AGENT); }
; __device__ __forceinline__ unsigned xb_add(unsigned* p, unsigned v) { return __hip_atomic_fetch_add(p, v, __ATOMIC_RELAXED, __HIP_MEMORY_SCOPE_AGENT); }
; #define XB_SPIN(cond, bar) do { unsigned _sp = 0; while (cond) { __builtin_amdgcn_s_sleep(1); \
;     if ((++_sp & 255u) == 0u) { if (xb_ld(&(bar)[XB_TMO])) break; if (_sp > XB_SPIN_CAP) { atomicAdd(&(bar)[XB_TMO], 1u); break; } } } } while (0)
; __device__ __forceinline__ void xcd_barrier(const XcdBarrier& b) {
;     asm volatile("s_waitcnt vmcnt(0)" ::: "memory");
;     __syncthreads();
;     if (threadIdx.x == 0) {
;         unsigned* bar = b.bar;
;         __builtin_amdgcn_s_waitcnt(0);
;         unsigned nloc = b.st[0], nx = b.st[1];
;         if (nloc == 0u) { xcd_barrier_complete(bar, b.x, nloc, nx); b.st[0] = nloc; b.st[1] = nx; }
;         const unsigned old = xb_add(&bar[XB_XSUB(b.x)], 1u);
;         const unsigned gen = old / nloc;
;         if (old + 1u == (gen + 1u) * nloc) {
;             __builtin_amdgcn_fence(__ATOMIC_RELEASE, "agent");
;             asm volatile("s_waitcnt vmcnt(0)" ::: "memory");
;             const unsigned og = xb_add(&bar[XB_TOP], 1u);
;             const unsigned tg = og / nx;
;             if (og + 1u == (tg + 1u) * nx) xb_add(&bar[XB_TOPGEN], 1u);
;             else XB_SPIN(xb_ld(&bar[XB_TOPGEN]) == tg, bar);
;             __builtin_amdgcn_fence(__ATOMIC_ACQUIRE, "agent");
;             xb_add(&bar[XB_XGEN(b.x)], 1u);
;             asm volatile("s_waitcnt vmcnt(0)" ::: "memory");
;         } else {
;             XB_SPIN(xb_ld(&bar[XB_XGEN(b.x)]) == gen, bar);
;             __builtin_amdgcn_fence(__ATOMIC_ACQUIRE, "agent");
;             asm volatile("s_waitcnt vmcnt(0)" ::: "memory");
;         }
.LBB0_1153:
	s_cmp_lt_i32 s92, 11
	s_cselect_b64 s[6:7], -1, 0
	s_cmp_gt_i32 s93, 10
	s_cselect_b64 s[0:1], -1, 0
	s_and_b64 s[0:1], s[6:7], s[0:1]
	s_andn2_b64 vcc, exec, s[0:1]
	s_cbranch_vccnz .LBB0_1226
	s_andn2_b64 vcc, exec, s[8:9]
	s_cbranch_vccnz .LBB0_1204
	s_waitcnt vmcnt(0)
	v_cmp_eq_u32_e32 vcc, 0, v254
	s_waitcnt vmcnt(0) lgkmcnt(0)
	s_barrier
	s_and_saveexec_b64 s[0:1], vcc
	s_cbranch_execz .LBB0_1203
	s_cmp_eq_u32 s98, 1
	s_cbranch_scc0 .Lxfull_10
	s_add_i32 s99, s99, 1
	s_and_b32 s4, s2, 7
	s_lshl_b32 s4, s4, 8
	s_add_u32 s4, s90, s4
	s_addc_u32 s5, s91, 0
	s_lshr_b32 s3, s2, 3
	v_mov_b32_e32 v0, s99
	v_mov_b32_e32 v1, s3
	v_lshlrev_b32_e32 v1, 2, v1
	global_store_dword v1, v0, s[4:5] offset:512
	buffer_inv sc1
	s_cmp_eq_u32 s3, 0
	s_cbranch_scc0 .Lxwait_10
	s_mov_b64 s[8:9], exec
	s_mov_b32 exec_lo, -1
	s_mov_b32 exec_hi, 0
	v_lshlrev_b32_e32 v2, 2, v251
	s_mov_b32 s3, 0

; __device__ __forceinline__ unsigned xb_ld(unsigned* p)              { return __hip_atomic_load(p, __ATOMIC_RELAXED, __HIP_MEMORY_SCOPE_AGENT); }
; __device__ __forceinline__ unsigned xb_add(unsigned* p, unsigned v) { return __hip_atomic_fetch_add(p, v, __ATOMIC_RELAXED, __HIP_MEMORY_SCOPE_AGENT); }
; #define XB_SPIN(cond, bar) do { unsigned _sp = 0; while (cond) { __builtin_amdgcn_s_sleep(1); \
;     if ((++_sp & 255u) == 0u) { if (xb_ld(&(bar)[XB_TMO])) break; if (_sp > XB_SPIN_CAP) { atomicAdd(&(bar)[XB_TMO], 1u); break; } } } } while (0)
; __device__ __forceinline__ void xcd_barrier(const XcdBarrier& b) {
;     asm volatile("s_waitcnt vmcnt(0)" ::: "memory");
;     __syncthreads();
;     if (threadIdx.x == 0) {
;         unsigned* bar = b.bar;
;         __builtin_amdgcn_s_waitcnt(0);
;         unsigned nloc = b.st[0], nx = b.st[1];
;         if (nloc == 0u) { xcd_barrier_complete(bar, b.x, nloc, nx); b.st[0] = nloc; b.st[1] = nx; }
;         const unsigned old = xb_add(&bar[XB_XSUB(b.x)], 1u);
;         const unsigned gen = old / nloc;
;         if (old + 1u == (gen + 1u) * nloc) {
;             __builtin_amdgcn_fence(__ATOMIC_RELEASE, "agent");
;             asm volatile("s_waitcnt vmcnt(0)" ::: "memory");
;             const unsigned og = xb_add(&bar[XB_TOP], 1u);
;             const unsigned tg = og / nx;
;             if (og + 1u == (tg + 1u) * nx) xb_add(&bar[XB_TOPGEN], 1u);
;             else XB_SPIN(xb_ld(&bar[XB_TOPGEN]) == tg, bar);
;             __builtin_amdgcn_fence(__ATOMIC_ACQUIRE, "agent");
;             xb_add(&bar[XB_XGEN(b.x)], 1u);
;             asm volatile("s_waitcnt vmcnt(0)" ::: "memory");
;         } else {
;             XB_SPIN(xb_ld(&bar[XB_XGEN(b.x)]) == gen, bar);
;             __builtin_amdgcn_fence(__ATOMIC_ACQUIRE, "agent");
;             asm volatile("s_waitcnt vmcnt(0)" ::: "memory");
;         }
.LBB0_1226:
	s_cmp_lt_i32 s92, 12
	s_cselect_b64 s[8:9], -1, 0
	s_cmp_gt_i32 s93, 11
	s_cselect_b64 s[0:1], -1, 0
	s_and_b64 s[0:1], s[8:9], s[0:1]
	s_andn2_b64 vcc, exec, s[0:1]
	s_cbranch_vccnz .LBB0_1323
	s_andn2_b64 vcc, exec, s[6:7]
	s_cbranch_vccnz .LBB0_1277
	s_waitcnt vmcnt(0)
	v_cmp_eq_u32_e32 vcc, 0, v254
	s_waitcnt vmcnt(0) lgkmcnt(0)
	s_barrier
	s_and_saveexec_b64 s[0:1], vcc
	s_cbranch_execz .LBB0_1276
	s_cmp_eq_u32 s98, 1
	s_cbranch_scc0 .Lxfull_11
	s_add_i32 s99, s99, 1
	s_and_b32 s4, s2, 7
	s_lshl_b32 s4, s4, 8
	s_add_u32 s4, s90, s4
	s_addc_u32 s5, s91, 0
	s_lshr_b32 s3, s2, 3
	v_mov_b32_e32 v0, s99
	v_mov_b32_e32 v1, s3
	v_lshlrev_b32_e32 v1, 2, v1
	global_store_dword v1, v0, s[4:5] offset:512
	buffer_inv sc1
	s_cmp_eq_u32 s3, 0
	s_cbranch_scc0 .Lxwait_11
	s_mov_b64 s[6:7], exec
	s_mov_b32 exec_lo, -1
	s_mov_b32 exec_hi, 0
	v_lshlrev_b32_e32 v2, 2, v251
	s_mov_b32 s3, 0

; __device__ __forceinline__ unsigned xb_ld(unsigned* p)              { return __hip_atomic_load(p, __ATOMIC_RELAXED, __HIP_MEMORY_SCOPE_AGENT); }
; __device__ __forceinline__ unsigned xb_add(unsigned* p, unsigned v) { return __hip_atomic_fetch_add(p, v, __ATOMIC_RELAXED, __HIP_MEMORY_SCOPE_AGENT); }
; #define XB_SPIN(cond, bar) do { unsigned _sp = 0; while (cond) { __builtin_amdgcn_s_sleep(1); \
;     if ((++_sp & 255u) == 0u) { if (xb_ld(&(bar)[XB_TMO])) break; if (_sp > XB_SPIN_CAP) { atomicAdd(&(bar)[XB_TMO], 1u); break; } } } } while (0)
; __device__ __forceinline__ void xcd_barrier(const XcdBarrier& b) {
;     asm volatile("s_waitcnt vmcnt(0)" ::: "memory");
;     __syncthreads();
;     if (threadIdx.x == 0) {
;         unsigned* bar = b.bar;
;         __builtin_amdgcn_s_waitcnt(0);
;         unsigned nloc = b.st[0], nx = b.st[1];
;         if (nloc == 0u) { xcd_barrier_complete(bar, b.x, nloc, nx); b.st[0] = nloc; b.st[1] = nx; }
;         const unsigned old = xb_add(&bar[XB_XSUB(b.x)], 1u);
;         const unsigned gen = old / nloc;
;         if (old + 1u == (gen + 1u) * nloc) {
;             __builtin_amdgcn_fence(__ATOMIC_RELEASE, "agent");
;             asm volatile("s_waitcnt vmcnt(0)" ::: "memory");
;             const unsigned og = xb_add(&bar[XB_TOP], 1u);
;             const unsigned tg = og / nx;
;             if (og + 1u == (tg + 1u) * nx) xb_add(&bar[XB_TOPGEN], 1u);
;             else XB_SPIN(xb_ld(&bar[XB_TOPGEN]) == tg, bar);
;             __builtin_amdgcn_fence(__ATOMIC_ACQUIRE, "agent");
;             xb_add(&bar[XB_XGEN(b.x)], 1u);
;             asm volatile("s_waitcnt vmcnt(0)" ::: "memory");
;         } else {
;             XB_SPIN(xb_ld(&bar[XB_XGEN(b.x)]) == gen, bar);
;             __builtin_amdgcn_fence(__ATOMIC_ACQUIRE, "agent");
;             asm volatile("s_waitcnt vmcnt(0)" ::: "memory");
;         }
.LBB0_1323:
	s_cmp_lt_i32 s92, 13
	s_cselect_b64 s[10:11], -1, 0
	s_cmp_gt_i32 s93, 12
	s_cselect_b64 s[0:1], -1, 0
	s_and_b64 s[0:1], s[10:11], s[0:1]
	s_andn2_b64 vcc, exec, s[0:1]
	s_cbranch_vccnz .LBB0_1504
	s_andn2_b64 vcc, exec, s[8:9]
	s_cbranch_vccnz .LBB0_1374
	s_waitcnt vmcnt(0)
	v_cmp_eq_u32_e32 vcc, 0, v254
	s_waitcnt vmcnt(0) lgkmcnt(0)
	s_barrier
	s_and_saveexec_b64 s[0:1], vcc
	s_cbranch_execz .LBB0_1373
	s_cmp_eq_u32 s98, 1
	s_cbranch_scc0 .Lxfull_12
	s_add_i32 s99, s99, 1
	s_and_b32 s4, s2, 7
	s_lshl_b32 s4, s4, 8
	s_add_u32 s4, s90, s4
	s_addc_u32 s5, s91, 0
	s_lshr_b32 s3, s2, 3
	v_mov_b32_e32 v0, s99
	v_mov_b32_e32 v1, s3
	v_lshlrev_b32_e32 v1, 2, v1
	global_store_dword v1, v0, s[4:5] offset:512
	buffer_inv sc1
	s_cmp_eq_u32 s3, 0
	s_cbranch_scc0 .Lxwait_12
	s_mov_b64 s[6:7], exec
	s_mov_b32 exec_lo, -1
	s_mov_b32 exec_hi, 0
	v_lshlrev_b32_e32 v2, 2, v251
	s_mov_b32 s3, 0

; __device__ __forceinline__ unsigned xb_ld(unsigned* p)              { return __hip_atomic_load(p, __ATOMIC_RELAXED, __HIP_MEMORY_SCOPE_AGENT); }
; __device__ __forceinline__ unsigned xb_add(unsigned* p, unsigned v) { return __hip_atomic_fetch_add(p, v, __ATOMIC_RELAXED, __HIP_MEMORY_SCOPE_AGENT); }
; #define XB_SPIN(cond, bar) do { unsigned _sp = 0; while (cond) { __builtin_amdgcn_s_sleep(1); \
;     if ((++_sp & 255u) == 0u) { if (xb_ld(&(bar)[XB_TMO])) break; if (_sp > XB_SPIN_CAP) { atomicAdd(&(bar)[XB_TMO], 1u); break; } } } } while (0)
; __device__ __forceinline__ void xcd_barrier(const XcdBarrier& b) {
;     asm volatile("s_waitcnt vmcnt(0)" ::: "memory");
;     __syncthreads();
;     if (threadIdx.x == 0) {
;         unsigned* bar = b.bar;
;         __builtin_amdgcn_s_waitcnt(0);
;         unsigned nloc = b.st[0], nx = b.st[1];
;         if (nloc == 0u) { xcd_barrier_complete(bar, b.x, nloc, nx); b.st[0] = nloc; b.st[1] = nx; }
;         const unsigned old = xb_add(&bar[XB_XSUB(b.x)], 1u);
;         const unsigned gen = old / nloc;
;         if (old + 1u == (gen + 1u) * nloc) {
;             __builtin_amdgcn_fence(__ATOMIC_RELEASE, "agent");
;             asm volatile("s_waitcnt vmcnt(0)" ::: "memory");
;             const unsigned og = xb_add(&bar[XB_TOP], 1u);
;             const unsigned tg = og / nx;
;             if (og + 1u == (tg + 1u) * nx) xb_add(&bar[XB_TOPGEN], 1u);
;             else XB_SPIN(xb_ld(&bar[XB_TOPGEN]) == tg, bar);
;             __builtin_amdgcn_fence(__ATOMIC_ACQUIRE, "agent");
;             xb_add(&bar[XB_XGEN(b.x)], 1u);
;             asm volatile("s_waitcnt vmcnt(0)" ::: "memory");
;         } else {
;             XB_SPIN(xb_ld(&bar[XB_XGEN(b.x)]) == gen, bar);
;             __builtin_amdgcn_fence(__ATOMIC_ACQUIRE, "agent");
;             asm volatile("s_waitcnt vmcnt(0)" ::: "memory");
;         }
.LBB0_1587:
	s_cmp_lt_i32 s92, 15
	s_cselect_b64 s[0:1], -1, 0
	s_cmp_gt_i32 s93, 14
	s_cselect_b64 s[4:5], -1, 0
	s_and_b64 s[4:5], s[0:1], s[4:5]
	v_readlane_b32 s64, v255, 4
	s_andn2_b64 vcc, exec, s[4:5]
	v_readlane_b32 s68, v255, 8
	v_readlane_b32 s69, v255, 9
	v_readlane_b32 s78, v255, 18
	v_readlane_b32 s79, v255, 19
	v_readlane_b32 s65, v255, 5
	v_readlane_b32 s66, v255, 6
	v_readlane_b32 s67, v255, 7
	v_readlane_b32 s70, v255, 10
	v_readlane_b32 s71, v255, 11
	v_readlane_b32 s72, v255, 12
	v_readlane_b32 s73, v255, 13
	v_readlane_b32 s74, v255, 14
	v_readlane_b32 s75, v255, 15
	v_readlane_b32 s76, v255, 16
	v_readlane_b32 s77, v255, 17
	s_cbranch_vccnz .LBB0_1648
	s_andn2_b64 vcc, exec, s[46:47]
	s_cbranch_vccnz .LBB0_1638
	s_waitcnt vmcnt(0)
	v_cmp_eq_u32_e32 vcc, 0, v254
	s_waitcnt vmcnt(0) lgkmcnt(0)
	s_barrier
	s_and_saveexec_b64 s[4:5], vcc
	s_cbranch_execz .LBB0_1637
	s_cmp_eq_u32 s98, 1
	s_cbranch_scc0 .Lxfull_14
	s_add_i32 s99, s99, 1
	s_and_b32 s6, s2, 7
	s_lshl_b32 s6, s6, 8
	s_add_u32 s6, s90, s6
	s_addc_u32 s7, s91, 0
	s_lshr_b32 s3, s2, 3
	v_mov_b32_e32 v0, s99
	v_mov_b32_e32 v1, s3
	v_lshlrev_b32_e32 v1, 2, v1
	global_store_dword v1, v0, s[6:7] offset:512
	buffer_inv sc1
	s_cmp_eq_u32 s3, 0
	s_cbranch_scc0 .Lxwait_14
	s_mov_b64 s[8:9], exec
	s_mov_b32 exec_lo, -1
	s_mov_b32 exec_hi, 0
	v_lshlrev_b32_e32 v2, 2, v251
	s_mov_b32 s3, 0

; __device__ __forceinline__ unsigned xb_ld(unsigned* p)              { return __hip_atomic_load(p, __ATOMIC_RELAXED, __HIP_MEMORY_SCOPE_AGENT); }
; __device__ __forceinline__ unsigned xb_add(unsigned* p, unsigned v) { return __hip_atomic_fetch_add(p, v, __ATOMIC_RELAXED, __HIP_MEMORY_SCOPE_AGENT); }
; #define XB_SPIN(cond, bar) do { unsigned _sp = 0; while (cond) { __builtin_amdgcn_s_sleep(1); \
;     if ((++_sp & 255u) == 0u) { if (xb_ld(&(bar)[XB_TMO])) break; if (_sp > XB_SPIN_CAP) { atomicAdd(&(bar)[XB_TMO], 1u); break; } } } } while (0)
; __device__ __forceinline__ void xcd_barrier(const XcdBarrier& b) {
;     asm volatile("s_waitcnt vmcnt(0)" ::: "memory");
;     __syncthreads();
;     if (threadIdx.x == 0) {
;         unsigned* bar = b.bar;
;         __builtin_amdgcn_s_waitcnt(0);
;         unsigned nloc = b.st[0], nx = b.st[1];
;         if (nloc == 0u) { xcd_barrier_complete(bar, b.x, nloc, nx); b.st[0] = nloc; b.st[1] = nx; }
;         const unsigned old = xb_add(&bar[XB_XSUB(b.x)], 1u);
;         const unsigned gen = old / nloc;
;         if (old + 1u == (gen + 1u) * nloc) {
;             __builtin_amdgcn_fence(__ATOMIC_RELEASE, "agent");
;             asm volatile("s_waitcnt vmcnt(0)" ::: "memory");
;             const unsigned og = xb_add(&bar[XB_TOP], 1u);
;             const unsigned tg = og / nx;
;             if (og + 1u == (tg + 1u) * nx) xb_add(&bar[XB_TOPGEN], 1u);
;             else XB_SPIN(xb_ld(&bar[XB_TOPGEN]) == tg, bar);
;             __builtin_amdgcn_fence(__ATOMIC_ACQUIRE, "agent");
;             xb_add(&bar[XB_XGEN(b.x)], 1u);
;             asm volatile("s_waitcnt vmcnt(0)" ::: "memory");
;         } else {
;             XB_SPIN(xb_ld(&bar[XB_XGEN(b.x)]) == gen, bar);
;             __builtin_amdgcn_fence(__ATOMIC_ACQUIRE, "agent");
;             asm volatile("s_waitcnt vmcnt(0)" ::: "memory");
;         }
.LBB0_1648:
	s_cmp_lt_i32 s92, 16
	s_cselect_b64 s[40:41], -1, 0
	s_cmp_gt_i32 s93, 15
	s_cselect_b64 s[4:5], -1, 0
	s_and_b64 s[4:5], s[40:41], s[4:5]
	s_andn2_b64 vcc, exec, s[4:5]
	s_cbranch_vccnz .LBB0_1773
	s_andn2_b64 vcc, exec, s[0:1]
	s_cbranch_vccnz .LBB0_1699
	s_waitcnt vmcnt(0)
	v_cmp_eq_u32_e32 vcc, 0, v254
	s_waitcnt vmcnt(0) lgkmcnt(0)
	s_barrier
	s_and_saveexec_b64 s[0:1], vcc
	s_cbranch_execz .LBB0_1698
	s_cmp_eq_u32 s98, 1
	s_cbranch_scc0 .Lxfull_15
	s_add_i32 s99, s99, 1
	s_and_b32 s4, s2, 7
	s_lshl_b32 s4, s4, 8
	s_add_u32 s4, s90, s4
	s_addc_u32 s5, s91, 0
	s_lshr_b32 s3, s2, 3
	v_mov_b32_e32 v0, s99
	v_mov_b32_e32 v1, s3
	v_lshlrev_b32_e32 v1, 2, v1
	global_store_dword v1, v0, s[4:5] offset:512
	buffer_inv sc1
	s_cmp_eq_u32 s3, 0
	s_cbranch_scc0 .Lxwait_15
	s_mov_b64 s[6:7], exec
	s_mov_b32 exec_lo, -1
	s_mov_b32 exec_hi, 0
	v_lshlrev_b32_e32 v2, 2, v251
	s_mov_b32 s3, 0

; __device__ __forceinline__ unsigned xb_ld(unsigned* p)              { return __hip_atomic_load(p, __ATOMIC_RELAXED, __HIP_MEMORY_SCOPE_AGENT); }
; __device__ __forceinline__ unsigned xb_add(unsigned* p, unsigned v) { return __hip_atomic_fetch_add(p, v, __ATOMIC_RELAXED, __HIP_MEMORY_SCOPE_AGENT); }
; #define XB_SPIN(cond, bar) do { unsigned _sp = 0; while (cond) { __builtin_amdgcn_s_sleep(1); \
;     if ((++_sp & 255u) == 0u) { if (xb_ld(&(bar)[XB_TMO])) break; if (_sp > XB_SPIN_CAP) { atomicAdd(&(bar)[XB_TMO], 1u); break; } } } } while (0)
; __device__ __forceinline__ void xcd_barrier(const XcdBarrier& b) {
;     asm volatile("s_waitcnt vmcnt(0)" ::: "memory");
;     __syncthreads();
;     if (threadIdx.x == 0) {
;         unsigned* bar = b.bar;
;         __builtin_amdgcn_s_waitcnt(0);
;         unsigned nloc = b.st[0], nx = b.st[1];
;         if (nloc == 0u) { xcd_barrier_complete(bar, b.x, nloc, nx); b.st[0] = nloc; b.st[1] = nx; }
;         const unsigned old = xb_add(&bar[XB_XSUB(b.x)], 1u);
;         const unsigned gen = old / nloc;
;         if (old + 1u == (gen + 1u) * nloc) {
;             __builtin_amdgcn_fence(__ATOMIC_RELEASE, "agent");
;             asm volatile("s_waitcnt vmcnt(0)" ::: "memory");
;             const unsigned og = xb_add(&bar[XB_TOP], 1u);
;             const unsigned tg = og / nx;
;             if (og + 1u == (tg + 1u) * nx) xb_add(&bar[XB_TOPGEN], 1u);
;             else XB_SPIN(xb_ld(&bar[XB_TOPGEN]) == tg, bar);
;             __builtin_amdgcn_fence(__ATOMIC_ACQUIRE, "agent");
;             xb_add(&bar[XB_XGEN(b.x)], 1u);
;             asm volatile("s_waitcnt vmcnt(0)" ::: "memory");
;         } else {
;             XB_SPIN(xb_ld(&bar[XB_XGEN(b.x)]) == gen, bar);
;             __builtin_amdgcn_fence(__ATOMIC_ACQUIRE, "agent");
;             asm volatile("s_waitcnt vmcnt(0)" ::: "memory");
;         }
.LBB0_1866:
	s_cmp_lt_i32 s92, 18
	s_cselect_b64 s[10:11], -1, 0
	s_cmp_gt_i32 s93, 17
	s_cselect_b64 s[0:1], -1, 0
	s_and_b64 s[0:1], s[10:11], s[0:1]
	s_andn2_b64 vcc, exec, s[0:1]
	s_cbranch_vccnz .LBB0_1939
	s_andn2_b64 vcc, exec, s[6:7]
	s_cbranch_vccnz .LBB0_1917
	s_waitcnt vmcnt(0)
	v_cmp_eq_u32_e32 vcc, 0, v254
	s_waitcnt vmcnt(0) lgkmcnt(0)
	s_barrier
	s_and_saveexec_b64 s[0:1], vcc
	s_cbranch_execz .LBB0_1916
	s_cmp_eq_u32 s98, 1
	s_cbranch_scc0 .Lxfull_17
	s_add_i32 s99, s99, 1
	s_and_b32 s4, s2, 7
	s_lshl_b32 s4, s4, 8
	s_add_u32 s4, s90, s4
	s_addc_u32 s5, s91, 0
	s_lshr_b32 s3, s2, 3
	v_mov_b32_e32 v0, s99
	v_mov_b32_e32 v1, s3
	v_lshlrev_b32_e32 v1, 2, v1
	global_store_dword v1, v0, s[4:5] offset:512
	buffer_inv sc1
	s_cmp_eq_u32 s3, 0
	s_cbranch_scc0 .Lxwait_17
	s_mov_b64 s[6:7], exec
	s_mov_b32 exec_lo, -1
	s_mov_b32 exec_hi, 0
	v_lshlrev_b32_e32 v2, 2, v251
	s_mov_b32 s3, 0

; __device__ __forceinline__ unsigned xb_ld(unsigned* p)              { return __hip_atomic_load(p, __ATOMIC_RELAXED, __HIP_MEMORY_SCOPE_AGENT); }
; __device__ __forceinline__ unsigned xb_add(unsigned* p, unsigned v) { return __hip_atomic_fetch_add(p, v, __ATOMIC_RELAXED, __HIP_MEMORY_SCOPE_AGENT); }
; #define XB_SPIN(cond, bar) do { unsigned _sp = 0; while (cond) { __builtin_amdgcn_s_sleep(1); \
;     if ((++_sp & 255u) == 0u) { if (xb_ld(&(bar)[XB_TMO])) break; if (_sp > XB_SPIN_CAP) { atomicAdd(&(bar)[XB_TMO], 1u); break; } } } } while (0)
; __device__ __forceinline__ void xcd_barrier(const XcdBarrier& b) {
;     asm volatile("s_waitcnt vmcnt(0)" ::: "memory");
;     __syncthreads();
;     if (threadIdx.x == 0) {
;         unsigned* bar = b.bar;
;         __builtin_amdgcn_s_waitcnt(0);
;         unsigned nloc = b.st[0], nx = b.st[1];
;         if (nloc == 0u) { xcd_barrier_complete(bar, b.x, nloc, nx); b.st[0] = nloc; b.st[1] = nx; }
;         const unsigned old = xb_add(&bar[XB_XSUB(b.x)], 1u);
;         const unsigned gen = old / nloc;
;         if (old + 1u == (gen + 1u) * nloc) {
;             __builtin_amdgcn_fence(__ATOMIC_RELEASE, "agent");
;             asm volatile("s_waitcnt vmcnt(0)" ::: "memory");
;             const unsigned og = xb_add(&bar[XB_TOP], 1u);
;             const unsigned tg = og / nx;
;             if (og + 1u == (tg + 1u) * nx) xb_add(&bar[XB_TOPGEN], 1u);
;             else XB_SPIN(xb_ld(&bar[XB_TOPGEN]) == tg, bar);
;             __builtin_amdgcn_fence(__ATOMIC_ACQUIRE, "agent");
;             xb_add(&bar[XB_XGEN(b.x)], 1u);
;             asm volatile("s_waitcnt vmcnt(0)" ::: "memory");
;         } else {
;             XB_SPIN(xb_ld(&bar[XB_XGEN(b.x)]) == gen, bar);
;             __builtin_amdgcn_fence(__ATOMIC_ACQUIRE, "agent");
;             asm volatile("s_waitcnt vmcnt(0)" ::: "memory");
;         }
.LBB0_1939:
	s_cmp_lt_i32 s92, 19
	s_cselect_b64 s[8:9], -1, 0
	s_cmp_gt_i32 s93, 18
	s_cselect_b64 s[0:1], -1, 0
	s_and_b64 s[0:1], s[8:9], s[0:1]
	s_andn2_b64 vcc, exec, s[0:1]
	s_cbranch_vccnz .LBB0_2036
	s_andn2_b64 vcc, exec, s[10:11]
	s_cbranch_vccnz .LBB0_1990
	s_waitcnt vmcnt(0)
	v_cmp_eq_u32_e32 vcc, 0, v254
	s_waitcnt vmcnt(0) lgkmcnt(0)
	s_barrier
	s_and_saveexec_b64 s[0:1], vcc
	s_cbranch_execz .LBB0_1989
	s_cmp_eq_u32 s98, 1
	s_cbranch_scc0 .Lxfull_18
	s_add_i32 s99, s99, 1
	s_and_b32 s4, s2, 7
	s_lshl_b32 s4, s4, 8
	s_add_u32 s4, s90, s4
	s_addc_u32 s5, s91, 0
	s_lshr_b32 s3, s2, 3
	v_mov_b32_e32 v0, s99
	v_mov_b32_e32 v1, s3
	v_lshlrev_b32_e32 v1, 2, v1
	global_store_dword v1, v0, s[4:5] offset:512
	buffer_inv sc1
	s_cmp_eq_u32 s3, 0
	s_cbranch_scc0 .Lxwait_18
	s_mov_b64 s[6:7], exec
	s_mov_b32 exec_lo, -1
	s_mov_b32 exec_hi, 0
	v_lshlrev_b32_e32 v2, 2, v251
	s_mov_b32 s3, 0

; __device__ __forceinline__ unsigned xb_ld(unsigned* p)              { return __hip_atomic_load(p, __ATOMIC_RELAXED, __HIP_MEMORY_SCOPE_AGENT); }
; __device__ __forceinline__ unsigned xb_add(unsigned* p, unsigned v) { return __hip_atomic_fetch_add(p, v, __ATOMIC_RELAXED, __HIP_MEMORY_SCOPE_AGENT); }
; #define XB_SPIN(cond, bar) do { unsigned _sp = 0; while (cond) { __builtin_amdgcn_s_sleep(1); \
;     if ((++_sp & 255u) == 0u) { if (xb_ld(&(bar)[XB_TMO])) break; if (_sp > XB_SPIN_CAP) { atomicAdd(&(bar)[XB_TMO], 1u); break; } } } } while (0)
; __device__ __forceinline__ void xcd_barrier(const XcdBarrier& b) {
;     asm volatile("s_waitcnt vmcnt(0)" ::: "memory");
;     __syncthreads();
;     if (threadIdx.x == 0) {
;         unsigned* bar = b.bar;
;         __builtin_amdgcn_s_waitcnt(0);
;         unsigned nloc = b.st[0], nx = b.st[1];
;         if (nloc == 0u) { xcd_barrier_complete(bar, b.x, nloc, nx); b.st[0] = nloc; b.st[1] = nx; }
;         const unsigned old = xb_add(&bar[XB_XSUB(b.x)], 1u);
;         const unsigned gen = old / nloc;
;         if (old + 1u == (gen + 1u) * nloc) {
;             __builtin_amdgcn_fence(__ATOMIC_RELEASE, "agent");
;             asm volatile("s_waitcnt vmcnt(0)" ::: "memory");
;             const unsigned og = xb_add(&bar[XB_TOP], 1u);
;             const unsigned tg = og / nx;
;             if (og + 1u == (tg + 1u) * nx) xb_add(&bar[XB_TOPGEN], 1u);
;             else XB_SPIN(xb_ld(&bar[XB_TOPGEN]) == tg, bar);
;             __builtin_amdgcn_fence(__ATOMIC_ACQUIRE, "agent");
;             xb_add(&bar[XB_XGEN(b.x)], 1u);
;             asm volatile("s_waitcnt vmcnt(0)" ::: "memory");
;         } else {
;             XB_SPIN(xb_ld(&bar[XB_XGEN(b.x)]) == gen, bar);
;             __builtin_amdgcn_fence(__ATOMIC_ACQUIRE, "agent");
;             asm volatile("s_waitcnt vmcnt(0)" ::: "memory");
;         }
.LBB0_2036:
	s_cmp_lt_i32 s92, 20
	s_cselect_b64 s[0:1], -1, 0
	s_cmp_gt_i32 s93, 19
	s_cselect_b64 s[4:5], -1, 0
	s_and_b64 s[0:1], s[0:1], s[4:5]
	s_andn2_b64 vcc, exec, s[0:1]
	s_cbranch_vccnz .LBB0_2090
	s_andn2_b64 vcc, exec, s[8:9]
	s_cbranch_vccnz .LBB0_2087
	s_waitcnt vmcnt(0)
	v_cmp_eq_u32_e32 vcc, 0, v254
	s_waitcnt vmcnt(0) lgkmcnt(0)
	s_barrier
	s_and_saveexec_b64 s[0:1], vcc
	s_cbranch_execz .LBB0_2086
	s_cmp_eq_u32 s98, 1
	s_cbranch_scc0 .Lxfull_19
	s_add_i32 s99, s99, 1
	s_and_b32 s4, s2, 7
	s_lshl_b32 s4, s4, 8
	s_add_u32 s4, s90, s4
	s_addc_u32 s5, s91, 0
	s_lshr_b32 s3, s2, 3
	v_mov_b32_e32 v0, s99
	v_mov_b32_e32 v1, s3
	v_lshlrev_b32_e32 v1, 2, v1
	global_store_dword v1, v0, s[4:5] offset:512
	buffer_inv sc1
	s_cmp_eq_u32 s3, 0
	s_cbranch_scc0 .Lxwait_19
	s_mov_b64 s[6:7], exec
	s_mov_b32 exec_lo, -1
	s_mov_b32 exec_hi, 0
	v_lshlrev_b32_e32 v2, 2, v251
	s_mov_b32 s3, 0
